# attention: PV prio 1 / QK prio 0 in main tile loop; NA and LRU: static s_setprio 1 for waves 4-7
# speedup vs baseline: 1.1344x; 1.0165x over previous
.LBB0_152:
	s_cmp_eq_u32 s34, 1
	s_cbranch_scc0 .Lna_prio_skip
	s_setprio 1

.LBB0_167:
	s_setprio 0
	s_mov_b64 s[2:3], 0
	s_movk_i32 s77, 0x3ff
	s_movk_i32 s80, 0xc00
	s_movk_i32 s81, 0x7ff
	s_movk_i32 s82, 0xfe00
.LBB0_168:
	s_andn2_b64 vcc, exec, s[2:3]
	s_cbranch_vccnz .LBB0_309
	v_readlane_b32 s2, v255, 20
	v_readlane_b32 s3, v255, 21
	s_lshl_b32 s2, s2, 2
	s_ashr_i32 s3, s2, 31
	s_lshl_b64 s[2:3], s[2:3], 2
	s_waitcnt lgkmcnt(0)
	s_add_u32 s2, s84, s2
	s_addc_u32 s3, s85, s3
	s_waitcnt vmcnt(13)
	v_mov_b32_e32 v0, 0x500000
	global_load_dwordx2 v[144:145], v0, s[2:3]
	s_cmpk_gt_i32 s44, 0xff
	s_cbranch_scc1 .LBB0_246
	v_readlane_b32 s2, v255, 20
	s_load_dwordx2 s[16:17], s[0:1], 0xb0
	s_mov_b32 s18, s2
	v_readlane_b32 s3, v255, 21
	s_lshl_b32 s2, s2, 3
	s_ashr_i32 s19, s18, 31
	v_writelane_b32 v255, s2, 24
	s_lshl_b64 s[2:3], s[18:19], 13
	v_writelane_b32 v255, s2, 25
	s_mov_b32 s12, s18
	s_nop 0
	v_writelane_b32 v255, s3, 26
	s_waitcnt lgkmcnt(0)
	s_add_u32 s2, s16, 0x510000
	v_writelane_b32 v255, s2, 27
	s_addc_u32 s2, s17, 0
	v_writelane_b32 v255, s2, 28
	s_lshl_b32 s2, s18, 9
	v_writelane_b32 v255, s12, 20
	s_ashr_i32 s3, s2, 31
	s_nop 0
	v_writelane_b32 v255, s13, 21
	s_lshl_b32 s12, s18, 10
	s_add_u32 s90, s16, 0xf000000
	s_addc_u32 s91, s17, 0
	v_writelane_b32 v255, s12, 29
	s_add_u32 s12, s16, 0x7000400
	s_addc_u32 s13, s17, 0
	v_writelane_b32 v255, s12, 30
	s_nop 1
	v_writelane_b32 v255, s13, 31
	s_nop 0
	v_readlane_b32 s13, v255, 8
	s_cmp_eq_u32 s13, 7
	s_cselect_b64 s[18:19], -1, 0
	v_writelane_b32 v255, s18, 32
	s_lshl_b32 s12, s13, 11
	s_add_i32 s12, s12, 0
	v_writelane_b32 v255, s19, 33
	v_writelane_b32 v255, s12, 34
	s_lshl_b32 s12, s13, 8
	s_lshl_b32 s18, s13, 4
	s_add_i32 s97, s12, 0
	s_ashr_i32 s19, s18, 31
	s_add_i32 s97, s97, 0x11000
	s_cmp_gt_i32 s13, 0
	s_cselect_b64 s[84:85], -1, 0
	s_cmp_gt_i32 s13, 1
	s_cselect_b64 s[38:39], -1, 0
	s_cmp_gt_i32 s13, 2
	s_cselect_b64 s[40:41], -1, 0
	s_cmp_gt_i32 s13, 3
	s_cselect_b64 s[42:43], -1, 0
	s_cmp_gt_i32 s13, 4
	s_cselect_b64 s[44:45], -1, 0
	s_cmp_gt_i32 s13, 5
	s_cselect_b64 s[46:47], -1, 0
	s_cmp_gt_i32 s13, 6
	v_readlane_b32 s12, v255, 7
	s_cselect_b64 s[48:49], -1, 0
	s_cmp_lt_u32 s12, 64
	s_cselect_b64 s[22:23], -1, 0
	s_cmp_lt_i32 s13, 7
	s_cselect_b64 s[34:35], -1, 0
	s_cmp_lt_i32 s13, 6
	s_cselect_b64 s[50:51], -1, 0
	s_cmp_lt_i32 s13, 5
	s_cselect_b64 s[52:53], -1, 0
	s_cmp_lt_i32 s13, 4
	v_writelane_b32 v255, s22, 35
	s_cselect_b64 s[54:55], -1, 0
	s_cmp_lt_i32 s13, 3
	v_writelane_b32 v255, s23, 36
	s_cselect_b64 s[56:57], -1, 0
	s_cmp_lt_i32 s13, 2
	s_cselect_b64 s[58:59], -1, 0
	s_cmp_lt_i32 s13, 1
	v_readlane_b32 s37, v255, 10
	s_cselect_b64 s[60:61], -1, 0
	s_bitcmp1_b32 s37, 0
	s_cselect_b64 s[92:93], -1, 0
	s_bitcmp1_b32 s96, 0
	s_cselect_b64 s[12:13], -1, 0
	v_writelane_b32 v255, s12, 37
	s_lshl_b64 s[86:87], s[18:19], 11
	s_mov_b64 s[78:79], s[18:19]
	v_writelane_b32 v255, s13, 38
	s_add_u32 s12, s16, 0x73c0400
	s_addc_u32 s13, s17, 0
	v_writelane_b32 v255, s12, 39
	s_lshl_b64 s[2:3], s[2:3], 2
	s_nop 0
	v_writelane_b32 v255, s13, 40
	v_writelane_b32 v255, s2, 41
	s_nop 1
	v_writelane_b32 v255, s3, 42
	v_readlane_b32 s99, v255, 8
	s_nop 0
	s_cmp_gt_u32 s99, 3
	s_cbranch_scc0 .Llru_prio_skip
	s_setprio 1
.Llru_prio_skip:
	s_branch .LBB0_172
.LBB0_171:
	v_readlane_b32 s2, v255, 37
	s_waitcnt vmcnt(0)
	v_readlane_b32 s3, v255, 38
	s_add_i32 s37, s37, s96
	s_xor_b64 s[92:93], s[92:93], s[2:3]
	s_cmpk_gt_i32 s37, 0xff
	s_waitcnt lgkmcnt(0)
	s_barrier
	s_cbranch_scc1 .LBB0_246

.LBB0_246:
	s_setprio 0
	v_readlane_b32 s63, v255, 10
	v_mov_b32_e32 v0, v192
	s_cmpk_lt_i32 s63, 0x400
	s_mov_b32 s37, 0
	s_cbranch_scc0 .LBB0_248
	s_abs_i32 s2, s96
	v_cvt_f32_u32_e32 v1, s2
	s_sub_i32 s3, s96, s63
	s_add_i32 s12, s3, 0x3ff
	s_sub_i32 s3, 0xfffffc01, s3
	v_rcp_iflag_f32_e32 v1, v1
	s_xor_b32 s14, s12, s96
	s_sub_i32 s13, 0, s2
	s_max_i32 s3, s12, s3
	v_mul_f32_e32 v1, 0x4f7ffffe, v1
	v_cvt_u32_f32_e32 v1, v1
	s_ashr_i32 s12, s14, 31
	v_readfirstlane_b32 s14, v1
	s_mul_i32 s13, s13, s14
	s_mul_hi_u32 s13, s14, s13
	s_add_i32 s14, s14, s13
	s_mul_hi_u32 s13, s3, s14
	s_mul_i32 s14, s13, s2
	s_sub_i32 s3, s3, s14
	s_add_i32 s16, s13, 1
	s_sub_i32 s14, s3, s2
	s_cmp_ge_u32 s3, s2
	s_cselect_b32 s13, s16, s13
	s_cselect_b32 s3, s14, s3
	s_add_i32 s14, s13, 1
	s_cmp_ge_u32 s3, s2
	s_cselect_b32 s2, s14, s13
	s_xor_b32 s2, s2, s12
	s_sub_i32 s37, s2, s12

.LBB0_270:
	s_waitcnt lgkmcnt(0)
	v_max_f32_e32 v1, v1, v1
	v_max_f32_e32 v0, v0, v0
	v_max_f32_e32 v69, v0, v1
	v_sub_f32_e32 v32, v32, v69
	v_sub_f32_e32 v16, v16, v69
	v_sub_f32_e32 v33, v33, v69
	v_sub_f32_e32 v68, v46, v69
	v_sub_f32_e32 v46, v17, v69
	v_exp_f32_e32 v16, v16
	v_exp_f32_e32 v17, v32
	v_sub_f32_e32 v34, v34, v69
	v_sub_f32_e32 v70, v47, v69
	v_sub_f32_e32 v47, v18, v69
	v_sub_f32_e32 v71, v19, v69
	v_exp_f32_e32 v18, v46
	v_exp_f32_e32 v19, v33
	v_sub_f32_e32 v35, v35, v69
	v_sub_f32_e32 v72, v20, v69
	v_sub_f32_e32 v73, v21, v69
	v_exp_f32_e32 v20, v47
	v_exp_f32_e32 v21, v34
	v_sub_f32_e32 v36, v36, v69
	v_sub_f32_e32 v74, v22, v69
	v_sub_f32_e32 v75, v23, v69
	v_exp_f32_e32 v22, v71
	v_exp_f32_e32 v23, v35
	v_sub_f32_e32 v37, v37, v69
	v_sub_f32_e32 v76, v24, v69
	v_sub_f32_e32 v77, v25, v69
	v_sub_f32_e32 v78, v26, v69
	v_sub_f32_e32 v79, v27, v69
	v_pk_add_f32 v[24:25], v[16:17], 0 op_sel_hi:[1,0]
	v_exp_f32_e32 v26, v72
	v_exp_f32_e32 v27, v36
	v_sub_f32_e32 v38, v38, v69
	v_sub_f32_e32 v80, v28, v69
	v_sub_f32_e32 v81, v29, v69
	v_pk_add_f32 v[24:25], v[18:19], v[24:25]
	v_exp_f32_e32 v28, v73
	v_exp_f32_e32 v29, v37
	v_sub_f32_e32 v39, v39, v69
	v_sub_f32_e32 v82, v30, v69
	v_sub_f32_e32 v83, v31, v69
	v_pk_add_f32 v[24:25], v[20:21], v[24:25]
	v_exp_f32_e32 v30, v74
	v_exp_f32_e32 v31, v38
	v_sub_f32_e32 v40, v40, v69
	v_pk_add_f32 v[24:25], v[22:23], v[24:25]
	v_exp_f32_e32 v32, v75
	v_exp_f32_e32 v33, v39
	v_sub_f32_e32 v41, v41, v69
	v_exp_f32_e32 v34, v76
	v_exp_f32_e32 v35, v40
	v_pk_add_f32 v[24:25], v[26:27], v[24:25]
	v_sub_f32_e32 v42, v42, v69
	v_exp_f32_e32 v36, v77
	v_exp_f32_e32 v37, v41
	v_pk_add_f32 v[24:25], v[28:29], v[24:25]
	v_sub_f32_e32 v43, v43, v69
	v_exp_f32_e32 v38, v78
	v_exp_f32_e32 v39, v42
	v_pk_add_f32 v[24:25], v[30:31], v[24:25]
	v_sub_f32_e32 v44, v44, v69
	v_exp_f32_e32 v40, v79
	v_exp_f32_e32 v41, v43
	v_pk_add_f32 v[24:25], v[32:33], v[24:25]
	v_sub_f32_e32 v45, v45, v69
	v_exp_f32_e32 v42, v80
	v_exp_f32_e32 v43, v44
	v_pk_add_f32 v[24:25], v[34:35], v[24:25]
	v_exp_f32_e32 v44, v81
	v_exp_f32_e32 v45, v45
	v_pk_add_f32 v[24:25], v[36:37], v[24:25]
	v_exp_f32_e32 v46, v82
	v_exp_f32_e32 v47, v68
	v_pk_add_f32 v[24:25], v[38:39], v[24:25]
	v_exp_f32_e32 v82, v83
	v_exp_f32_e32 v83, v70
	v_pk_add_f32 v[24:25], v[40:41], v[24:25]
	s_add_i32 s64, s64, 1
	v_exp_f32_e64 v0, -v69
	v_pk_add_f32 v[24:25], v[42:43], v[24:25]
	s_cmp_lt_u32 s64, s37
	v_pk_add_f32 v[24:25], v[44:45], v[24:25]
	s_cselect_b32 s12, s96, 0
	v_pk_add_f32 v[24:25], v[46:47], v[24:25]
	s_add_i32 s27, s12, s27
	v_pk_add_f32 v[24:25], v[82:83], v[24:25]
	s_ashr_i32 s12, s27, 6
	s_bfe_u32 s54, s27, 0x20004
	v_mul_f32_e32 v0, 0, v0
	v_pk_add_f32 v[24:25], v[24:25], v[24:25] op_sel:[0,1] op_sel_hi:[1,0]
	s_lshl_b32 s36, s12, 4
	s_lshl_b32 s53, s54, 1
	v_mov_b32_e32 v68, v0
	v_mov_b32_e32 v25, v189
	s_or_b32 s53, s53, s36
	s_lshl_b32 s36, s63, 7
	s_and_b32 s55, s58, 0x780
	v_pk_add_f32 v[206:207], v[68:69], v[24:25]
	v_cvt_pk_bf16_f32 v68, v16, v18
	s_and_b32 s36, s36, 0x1800
	v_add_lshl_u32 v16, v158, s55, 2
	v_sub_u32_e32 v16, s36, v16
	v_cvt_pk_bf16_f32 v69, v20, v22
	v_cvt_pk_bf16_f32 v70, v26, v28
	v_cvt_pk_bf16_f32 v71, v30, v32
	v_cvt_pk_bf16_f32 v76, v17, v19
	v_cvt_pk_bf16_f32 v77, v21, v23
	v_cvt_pk_bf16_f32 v78, v27, v29
	v_cvt_pk_bf16_f32 v79, v31, v33
	v_add_u32_e32 v167, v215, v16
	ds_read_b128 v[16:19], v64 offset:20480
	ds_read_b128 v[20:23], v65 offset:20480
	ds_read_b128 v[24:27], v66 offset:20480
	ds_read_b128 v[28:31], v67 offset:20480
	s_lshl_b32 s54, s54, 7
	s_lshl_b32 s12, s12, 9
	v_mov_b32_e32 v1, v0
	v_mov_b32_e32 v2, v0
	v_mov_b32_e32 v3, v0
	v_mov_b32_e32 v4, v0
	v_mov_b32_e32 v5, v0
	v_mov_b32_e32 v6, v0
	v_mov_b32_e32 v7, v0
	v_mov_b32_e32 v8, v0
	v_mov_b32_e32 v9, v0
	v_mov_b32_e32 v10, v0
	v_mov_b32_e32 v11, v0
	v_mov_b32_e32 v12, v0
	v_mov_b32_e32 v13, v0
	v_mov_b32_e32 v14, v0
	v_mov_b32_e32 v15, v0
	s_mov_b32 s23, 0
	s_sub_i32 s36, s62, s55
	s_or_b32 s12, s54, s12
	v_cvt_pk_bf16_f32 v72, v34, v36
	v_cvt_pk_bf16_f32 v73, v38, v40
	v_cvt_pk_bf16_f32 v74, v42, v44
	v_cvt_pk_bf16_f32 v75, v46, v82
	v_cvt_pk_bf16_f32 v80, v35, v37
	v_cvt_pk_bf16_f32 v81, v39, v41
	v_cvt_pk_bf16_f32 v82, v43, v45
	v_cvt_pk_bf16_f32 v83, v47, v83
	v_mfma_f32_32x32x16_bf16 v[32:47], v[56:59], v[68:71], v[0:15]
	v_mfma_f32_32x32x16_bf16 v[32:47], v[48:51], v[72:75], v[32:47]
	v_mfma_f32_32x32x16_bf16 v[32:47], v[60:63], v[76:79], v[32:47]
	v_mfma_f32_32x32x16_bf16 v[32:47], v[52:55], v[80:83], v[32:47]
	s_add_i32 s54, s33, 0x8000
	s_and_b32 s54, s54, 0x18000
	v_add_u32_e32 v48, s54, v149
	v_add_u32_e32 v49, v48, v157
	ds_read_b128 v[132:135], v49
	ds_read_b128 v[116:119], v49 offset:4096
	v_add_u32_e32 v49, v48, v193
	ds_read_b128 v[136:139], v49
	ds_read_b128 v[120:123], v49 offset:4096
	v_add_u32_e32 v49, v48, v208
	v_add_u32_e32 v48, v48, v209
	ds_read_b128 v[140:143], v49
	ds_read_b128 v[124:127], v49 offset:4096
	ds_read_b128 v[128:131], v48
	ds_read_b128 v[112:115], v48 offset:4096
	ds_read_b128 v[84:87], v64 offset:24576
	ds_read_b128 v[88:91], v65 offset:24576
	ds_read_b128 v[92:95], v66 offset:24576
	ds_read_b128 v[216:219], v67 offset:24576
	s_waitcnt lgkmcnt(0)
	v_mfma_f32_32x32x16_bf16 v[48:63], v[16:19], v[68:71], v[0:15]
	v_mfma_f32_32x32x16_bf16 v[48:63], v[20:23], v[72:75], v[48:63]
	v_mfma_f32_32x32x16_bf16 v[48:63], v[24:27], v[76:79], v[48:63]
	v_mfma_f32_32x32x16_bf16 v[48:63], v[28:31], v[80:83], v[48:63]
	ds_read_b128 v[220:223], v64 offset:28672
	ds_read_b128 v[234:237], v65 offset:28672
	ds_read_b128 v[238:241], v66 offset:28672
	ds_read_b128 v[64:67], v67 offset:28672
	v_mfma_f32_32x32x16_bf16 v[16:31], v[84:87], v[68:71], v[0:15]
	v_mfma_f32_32x32x16_bf16 v[16:31], v[88:91], v[72:75], v[16:31]
	v_mfma_f32_32x32x16_bf16 v[16:31], v[92:95], v[76:79], v[16:31]
	v_mfma_f32_32x32x16_bf16 v[16:31], v[216:219], v[80:83], v[16:31]
	s_waitcnt lgkmcnt(0)
	v_mfma_f32_32x32x16_bf16 v[0:15], v[220:223], v[68:71], v[0:15]
	s_waitcnt lgkmcnt(0)
	s_barrier
	s_add_i32 s65, s33, 0x10000
	s_mov_b32 s33, 0
	v_mfma_f32_32x32x16_bf16 v[0:15], v[234:237], v[72:75], v[0:15]
	v_mfma_f32_32x32x16_bf16 v[0:15], v[238:241], v[76:79], v[0:15]
	v_mfma_f32_32x32x16_bf16 v[0:15], v[64:67], v[80:83], v[0:15]
	s_setprio 0
	s_cmp_gt_u32 s36, 0xfffffeec
	s_mov_b64 s[54:55], -1
	s_cbranch_scc0 .LBB0_272

.LBB0_278:
	s_add_i32 s54, s33, 1
	s_setprio 1
	s_and_b64 vcc, exec, s[42:43]
	s_cbranch_vccnz .LBB0_280

.Lattn_tail:
	s_mov_b32 s33, s54
	s_setprio 0
	s_cmp_gt_u32 s36, 0xfffffeec
	s_mov_b64 s[54:55], -1
	s_cbranch_scc1 .LBB0_271
	s_branch .LBB0_272

.LBB0_283:
	s_waitcnt vmcnt(8) lgkmcnt(0)
	s_barrier
	s_add_i32 s54, s33, 1
	s_setprio 1
	s_and_b64 vcc, exec, s[42:43]
	s_cbranch_vccz .LBB0_279
	s_branch .LBB0_280
